# the tile's LDS-DMA pieces also issued behind the first QK MFMA and its K reads (tile head starts with LDS reads)
# baseline (speedup 1.0000x reference)
.Lcj_common_0:
	s_waitcnt lgkmcnt(0)
	s_mov_b32 s89, s88
	s_mov_b32 s88, s90
	s_mov_b32 s90, 0
	s_add_i32 s4, s4, 1
	s_add_i32 s49, s49, 0x8000
	v_lshl_add_u64 v[166:167], v[166:167], 0, s[10:11]
	v_lshl_add_u64 v[164:165], v[164:165], 0, s[10:11]
	s_cmp_eq_u32 s49, 0x238000
	s_barrier
	s_cbranch_scc1 .LBB0_1455

.LBB0_1451:
	s_add_i32 s34, s49, 0xfffe8000
	s_and_b32 s34, s34, 0x18000
	s_add_i32 s34, s34, 0
	v_add3_u32 v84, s34, v177, v176
	ds_read_b128 v[80:83], v84
	ds_read_b128 v[184:187], v84 offset:512
	v_add3_u32 v85, s34, v178, v176
	v_add3_u32 v84, s34, v179, v176
	v_add_u32_e32 v200, s34, v168
	v_add_u32_e32 v201, s34, v169
	s_and_b64 vcc, exec, s[26:27]
	s_waitcnt lgkmcnt(0)
	v_mfma_f32_32x32x16_bf16 v[96:111], v[80:83], v[112:115], v[0:15]
	ds_read_b128 v[80:83], v85 offset:2048
	ds_read_b128 v[188:191], v85 offset:2560
	v_add3_u32 v85, s34, v180, v176
	s_mov_b64 s[34:35], -1
	ds_read_b128 v[192:195], v84 offset:4608
	s_cbranch_vccnz .Lcjd_skip_0
	s_and_b32 s99, s49, 0x18000
	v_add_u32_e32 v208, s99, v182
	v_add_u32_e32 v223, 0x4000, v208
	v_readfirstlane_b32 s99, v208
	s_mov_b32 m0, s99
	v_readfirstlane_b32 s99, v223
	v_add_u32_e32 v208, 0x6000, v208
	global_load_lds_dwordx4 v[164:165], off
	s_mov_b32 m0, s99
	v_readfirstlane_b32 s99, v208
	global_load_lds_dwordx4 v[166:167], off
	v_lshl_add_u64 v[166:167], v[166:167], 0, s[10:11]
	s_mov_b32 m0, s99
	s_nop 0
	global_load_lds_dwordx4 v[166:167], off

.Lcjh_done_0:
	s_waitcnt lgkmcnt(0)
	v_mfma_f32_32x32x16_bf16 v[96:111], v[80:83], v[116:119], v[96:111]
	ds_read_b128 v[80:83], v84 offset:4096
	s_waitcnt lgkmcnt(0)
	v_mfma_f32_32x32x16_bf16 v[96:111], v[80:83], v[120:123], v[96:111]
	ds_read_b128 v[80:83], v85 offset:6144
	ds_read_b128 v[196:199], v85 offset:6656
	s_waitcnt lgkmcnt(0)
	v_mfma_f32_32x32x16_bf16 v[96:111], v[80:83], v[124:127], v[96:111]
	v_mfma_f32_32x32x16_bf16 v[80:95], v[184:187], v[112:115], v[0:15]
	ds_read_b128 v[184:187], v200 offset:16384
	s_nop 9
	v_exp_f32_e32 v96, v96
	v_exp_f32_e32 v97, v97
	v_exp_f32_e32 v98, v98
	v_exp_f32_e32 v99, v99
	v_exp_f32_e32 v100, v100
	v_exp_f32_e32 v101, v101
	v_mfma_f32_32x32x16_bf16 v[80:95], v[188:191], v[116:119], v[80:95]
	v_exp_f32_e32 v102, v102
	v_exp_f32_e32 v103, v103
	v_cvt_pk_bf16_f32 v188, v96, v97
	v_cvt_pk_bf16_f32 v189, v98, v99
	v_cvt_pk_bf16_f32 v190, v100, v101
	v_cvt_pk_bf16_f32 v191, v102, v103
	v_exp_f32_e32 v104, v104
	v_mfma_f32_32x32x16_bf16 v[80:95], v[192:195], v[120:123], v[80:95]
	ds_read_b128 v[192:195], v200 offset:17408
	v_exp_f32_e32 v105, v105
	v_exp_f32_e32 v106, v106
	v_exp_f32_e32 v107, v107
	v_exp_f32_e32 v108, v108
	v_exp_f32_e32 v109, v109
	v_exp_f32_e32 v110, v110
	v_mfma_f32_32x32x16_bf16 v[80:95], v[196:199], v[124:127], v[80:95]
	v_exp_f32_e32 v111, v111
	s_waitcnt lgkmcnt(0)
	v_mfma_f32_32x32x16_bf16 v[64:79], v[184:187], v[188:191], v[64:79]
	ds_read_b128 v[184:187], v201 offset:16896
	ds_read_b128 v[196:199], v201 offset:17920
	s_nop 6
	v_exp_f32_e32 v80, v80
	v_exp_f32_e32 v81, v81
	v_exp_f32_e32 v82, v82
	v_exp_f32_e32 v83, v83
	v_exp_f32_e32 v84, v84
	v_exp_f32_e32 v85, v85
	s_waitcnt lgkmcnt(0)
	v_mfma_f32_32x32x16_bf16 v[48:63], v[184:187], v[188:191], v[48:63]
	ds_read_b128 v[184:187], v200 offset:20480
	v_exp_f32_e32 v86, v86
	v_exp_f32_e32 v87, v87
	v_exp_f32_e32 v88, v88
	v_exp_f32_e32 v89, v89
	v_exp_f32_e32 v90, v90
	v_exp_f32_e32 v91, v91
	v_mfma_f32_32x32x16_bf16 v[32:47], v[192:195], v[188:191], v[32:47]
	ds_read_b128 v[192:195], v200 offset:21504
	v_exp_f32_e32 v92, v92
	v_exp_f32_e32 v93, v93
	v_exp_f32_e32 v94, v94
	v_exp_f32_e32 v95, v95
	v_mfma_f32_32x32x16_bf16 v[16:31], v[196:199], v[188:191], v[16:31]
	v_cvt_pk_bf16_f32 v188, v104, v105
	v_cvt_pk_bf16_f32 v189, v106, v107
	v_cvt_pk_bf16_f32 v190, v108, v109
	v_cvt_pk_bf16_f32 v191, v110, v111
	s_waitcnt lgkmcnt(0)
	s_nop 0
	v_mfma_f32_32x32x16_bf16 v[64:79], v[184:187], v[188:191], v[64:79]
	ds_read_b128 v[184:187], v201 offset:20992
	ds_read_b128 v[196:199], v201 offset:22016
	s_waitcnt lgkmcnt(0)
	v_mfma_f32_32x32x16_bf16 v[48:63], v[184:187], v[188:191], v[48:63]
	ds_read_b128 v[184:187], v200 offset:24576
	v_mfma_f32_32x32x16_bf16 v[32:47], v[192:195], v[188:191], v[32:47]
	ds_read_b128 v[192:195], v200 offset:25600
	v_mfma_f32_32x32x16_bf16 v[16:31], v[196:199], v[188:191], v[16:31]
	v_cvt_pk_bf16_f32 v188, v80, v81
	v_cvt_pk_bf16_f32 v189, v82, v83
	v_cvt_pk_bf16_f32 v190, v84, v85
	v_cvt_pk_bf16_f32 v191, v86, v87
	s_waitcnt lgkmcnt(0)
	s_nop 0
	v_mfma_f32_32x32x16_bf16 v[64:79], v[184:187], v[188:191], v[64:79]
	ds_read_b128 v[184:187], v201 offset:25088
	ds_read_b128 v[196:199], v201 offset:26112
	s_waitcnt lgkmcnt(0)
	v_mfma_f32_32x32x16_bf16 v[48:63], v[184:187], v[188:191], v[48:63]
	ds_read_b128 v[184:187], v200 offset:28672
	v_mfma_f32_32x32x16_bf16 v[32:47], v[192:195], v[188:191], v[32:47]
	ds_read_b128 v[192:195], v200 offset:29696
	v_mfma_f32_32x32x16_bf16 v[16:31], v[196:199], v[188:191], v[16:31]
	v_cvt_pk_bf16_f32 v188, v88, v89
	v_cvt_pk_bf16_f32 v189, v90, v91
	v_cvt_pk_bf16_f32 v190, v92, v93
	v_cvt_pk_bf16_f32 v191, v94, v95
	s_waitcnt lgkmcnt(0)
	s_nop 0
	v_mfma_f32_32x32x16_bf16 v[64:79], v[184:187], v[188:191], v[64:79]
	ds_read_b128 v[184:187], v201 offset:29184
	ds_read_b128 v[196:199], v201 offset:30208
	s_waitcnt lgkmcnt(0)
	v_mfma_f32_32x32x16_bf16 v[48:63], v[184:187], v[188:191], v[48:63]
	v_mfma_f32_32x32x16_bf16 v[32:47], v[192:195], v[188:191], v[32:47]
	v_mfma_f32_32x32x16_bf16 v[16:31], v[196:199], v[188:191], v[16:31]
	s_cbranch_vccz .Lcj_cnt_0
	s_waitcnt vmcnt(0)
	s_branch .LBB0_1448

.Lcj_common_1:
	s_waitcnt lgkmcnt(0)
	s_mov_b32 s89, s88
	s_mov_b32 s88, s90
	s_mov_b32 s90, 0
	s_add_i32 s4, s4, 1
	s_add_i32 s22, s22, 0x8000
	v_lshl_add_u64 v[148:149], v[148:149], 0, s[10:11]
	v_lshl_add_u64 v[150:151], v[150:151], 0, s[10:11]
	s_cmp_lg_u32 s22, 0x238000
	s_barrier
	s_cbranch_scc0 .LBB0_1446

.LBB0_1459:
	s_add_i32 s18, s22, 0xfffe8000
	s_and_b32 s18, s18, 0x18000
	s_add_i32 s18, s18, 0
	v_add3_u32 v84, s18, v177, v176
	ds_read_b128 v[80:83], v84
	ds_read_b128 v[152:155], v84 offset:512
	v_add3_u32 v85, s18, v178, v176
	v_add3_u32 v84, s18, v179, v176
	v_add_u32_e32 v209, s18, v168
	v_add_u32_e32 v211, s18, v169
	s_and_b64 vcc, exec, s[16:17]
	s_waitcnt lgkmcnt(0)
	v_mfma_f32_32x32x16_bf16 v[96:111], v[80:83], v[112:115], v[0:15]
	ds_read_b128 v[80:83], v85 offset:2048
	ds_read_b128 v[156:159], v85 offset:2560
	v_add3_u32 v85, s18, v180, v176
	s_mov_b64 s[18:19], -1
	ds_read_b128 v[160:163], v84 offset:4608
	s_cbranch_vccnz .Lcjd_skip_1
	s_and_b32 s99, s22, 0x18000
	v_add_u32_e32 v208, s99, v182
	v_add_u32_e32 v223, 0x4000, v208
	v_readfirstlane_b32 s99, v208
	s_mov_b32 m0, s99
	v_readfirstlane_b32 s99, v223
	v_add_u32_e32 v208, 0x6000, v208
	global_load_lds_dwordx4 v[150:151], off
	s_mov_b32 m0, s99
	v_readfirstlane_b32 s99, v208
	global_load_lds_dwordx4 v[148:149], off
	v_lshl_add_u64 v[148:149], v[148:149], 0, s[10:11]
	s_mov_b32 m0, s99
	s_nop 0
	global_load_lds_dwordx4 v[148:149], off

.Lcjh_done_1:
	s_waitcnt lgkmcnt(0)
	v_mfma_f32_32x32x16_bf16 v[96:111], v[80:83], v[116:119], v[96:111]
	ds_read_b128 v[80:83], v84 offset:4096
	s_waitcnt lgkmcnt(0)
	v_mfma_f32_32x32x16_bf16 v[96:111], v[80:83], v[120:123], v[96:111]
	ds_read_b128 v[80:83], v85 offset:6144
	ds_read_b128 v[218:221], v85 offset:6656
	s_waitcnt lgkmcnt(0)
	v_mfma_f32_32x32x16_bf16 v[96:111], v[80:83], v[124:127], v[96:111]
	v_mfma_f32_32x32x16_bf16 v[80:95], v[152:155], v[112:115], v[0:15]
	ds_read_b128 v[152:155], v209 offset:16384
	s_nop 9
	v_exp_f32_e32 v96, v96
	v_exp_f32_e32 v97, v97
	v_exp_f32_e32 v98, v98
	v_exp_f32_e32 v99, v99
	v_exp_f32_e32 v100, v100
	v_exp_f32_e32 v101, v101
	v_mfma_f32_32x32x16_bf16 v[80:95], v[156:159], v[116:119], v[80:95]
	v_exp_f32_e32 v102, v102
	v_exp_f32_e32 v103, v103
	v_cvt_pk_bf16_f32 v156, v96, v97
	v_cvt_pk_bf16_f32 v157, v98, v99
	v_cvt_pk_bf16_f32 v158, v100, v101
	v_cvt_pk_bf16_f32 v159, v102, v103
	v_exp_f32_e32 v104, v104
	v_mfma_f32_32x32x16_bf16 v[80:95], v[160:163], v[120:123], v[80:95]
	ds_read_b128 v[160:163], v209 offset:17408
	v_exp_f32_e32 v105, v105
	v_exp_f32_e32 v106, v106
	v_exp_f32_e32 v107, v107
	v_exp_f32_e32 v108, v108
	v_exp_f32_e32 v109, v109
	v_exp_f32_e32 v110, v110
	v_mfma_f32_32x32x16_bf16 v[80:95], v[218:221], v[124:127], v[80:95]
	v_exp_f32_e32 v111, v111
	s_waitcnt lgkmcnt(0)
	v_mfma_f32_32x32x16_bf16 v[64:79], v[152:155], v[156:159], v[64:79]
	ds_read_b128 v[152:155], v211 offset:16896
	ds_read_b128 v[218:221], v211 offset:17920
	s_nop 6
	v_exp_f32_e32 v80, v80
	v_exp_f32_e32 v81, v81
	v_exp_f32_e32 v82, v82
	v_exp_f32_e32 v83, v83
	v_exp_f32_e32 v84, v84
	v_exp_f32_e32 v85, v85
	s_waitcnt lgkmcnt(0)
	v_mfma_f32_32x32x16_bf16 v[48:63], v[152:155], v[156:159], v[48:63]
	ds_read_b128 v[152:155], v209 offset:20480
	v_exp_f32_e32 v86, v86
	v_exp_f32_e32 v87, v87
	v_exp_f32_e32 v88, v88
	v_exp_f32_e32 v89, v89
	v_exp_f32_e32 v90, v90
	v_exp_f32_e32 v91, v91
	v_mfma_f32_32x32x16_bf16 v[32:47], v[160:163], v[156:159], v[32:47]
	ds_read_b128 v[160:163], v209 offset:21504
	v_exp_f32_e32 v92, v92
	v_exp_f32_e32 v93, v93
	v_exp_f32_e32 v94, v94
	v_exp_f32_e32 v95, v95
	v_mfma_f32_32x32x16_bf16 v[16:31], v[218:221], v[156:159], v[16:31]
	v_cvt_pk_bf16_f32 v156, v104, v105
	v_cvt_pk_bf16_f32 v157, v106, v107
	v_cvt_pk_bf16_f32 v158, v108, v109
	v_cvt_pk_bf16_f32 v159, v110, v111
	s_waitcnt lgkmcnt(0)
	s_nop 0
	v_mfma_f32_32x32x16_bf16 v[64:79], v[152:155], v[156:159], v[64:79]
	ds_read_b128 v[152:155], v211 offset:20992
	ds_read_b128 v[218:221], v211 offset:22016
	s_waitcnt lgkmcnt(0)
	v_mfma_f32_32x32x16_bf16 v[48:63], v[152:155], v[156:159], v[48:63]
	ds_read_b128 v[152:155], v209 offset:24576
	v_mfma_f32_32x32x16_bf16 v[32:47], v[160:163], v[156:159], v[32:47]
	ds_read_b128 v[160:163], v209 offset:25600
	v_mfma_f32_32x32x16_bf16 v[16:31], v[218:221], v[156:159], v[16:31]
	v_cvt_pk_bf16_f32 v156, v80, v81
	v_cvt_pk_bf16_f32 v157, v82, v83
	v_cvt_pk_bf16_f32 v158, v84, v85
	v_cvt_pk_bf16_f32 v159, v86, v87
	s_waitcnt lgkmcnt(0)
	s_nop 0
	v_mfma_f32_32x32x16_bf16 v[64:79], v[152:155], v[156:159], v[64:79]
	ds_read_b128 v[152:155], v211 offset:25088
	ds_read_b128 v[218:221], v211 offset:26112
	s_waitcnt lgkmcnt(0)
	v_mfma_f32_32x32x16_bf16 v[48:63], v[152:155], v[156:159], v[48:63]
	ds_read_b128 v[152:155], v209 offset:28672
	v_mfma_f32_32x32x16_bf16 v[32:47], v[160:163], v[156:159], v[32:47]
	ds_read_b128 v[160:163], v209 offset:29696
	v_mfma_f32_32x32x16_bf16 v[16:31], v[218:221], v[156:159], v[16:31]
	v_cvt_pk_bf16_f32 v156, v88, v89
	v_cvt_pk_bf16_f32 v157, v90, v91
	v_cvt_pk_bf16_f32 v158, v92, v93
	v_cvt_pk_bf16_f32 v159, v94, v95
	s_waitcnt lgkmcnt(0)
	s_nop 0
	v_mfma_f32_32x32x16_bf16 v[64:79], v[152:155], v[156:159], v[64:79]
	ds_read_b128 v[152:155], v211 offset:29184
	ds_read_b128 v[218:221], v211 offset:30208
	s_waitcnt lgkmcnt(0)
	v_mfma_f32_32x32x16_bf16 v[48:63], v[152:155], v[156:159], v[48:63]
	v_mfma_f32_32x32x16_bf16 v[32:47], v[160:163], v[156:159], v[32:47]
	v_mfma_f32_32x32x16_bf16 v[16:31], v[218:221], v[156:159], v[16:31]
	s_cbranch_vccz .Lcj_cnt_1
	s_waitcnt vmcnt(0)
	s_branch .LBB0_1456
